# v70 + batched waits on transposing LDS reads in the GLA chunk phases (one lgkmcnt wait per run instead of per read)
# baseline (speedup 1.0000x reference)
.LBB0_608:
	s_or_b64 exec, exec, s[86:87]
	v_add_u32_e32 v0, v73, v84
	ds_write_b128 v0, v[4:7]
	v_add_u32_e32 v0, v73, v85
	ds_write_b128 v0, v[12:15]
	v_add_u32_e32 v0, v73, v86
	ds_write_b128 v0, v[8:11]
	v_add_u32_e32 v0, v73, v87
	ds_write_b128 v0, v[20:23]
	s_waitcnt lgkmcnt(0)
	s_barrier
	ds_read_b64_tr_b16 v[0:1], v88
	ds_read_b64_tr_b16 v[2:3], v89
	ds_read_b64_tr_b16 v[4:5], v90
	ds_read_b64_tr_b16 v[6:7], v91
	ds_read_b64_tr_b16 v[8:9], v92
	ds_read_b64_tr_b16 v[10:11], v93
	ds_read_b64_tr_b16 v[16:17], v94
	ds_read_b64_tr_b16 v[18:19], v95
	ds_read_b64_tr_b16 v[24:25], v96
	ds_read_b64_tr_b16 v[26:27], v97
	ds_read_b64_tr_b16 v[174:175], v98
	ds_read_b64_tr_b16 v[176:177], v99
	ds_read_b64_tr_b16 v[182:183], v100
	ds_read_b64_tr_b16 v[184:185], v101
	ds_read_b64_tr_b16 v[190:191], v102
	ds_read_b64_tr_b16 v[192:193], v103
	ds_read_b64_tr_b16 v[198:199], v104
	ds_read_b64_tr_b16 v[200:201], v105
	ds_read_b64_tr_b16 v[206:207], v106
	ds_read_b64_tr_b16 v[208:209], v107
	s_waitcnt lgkmcnt(0)
	s_nop 0
	v_mfma_f32_16x16x32_bf16 v[12:15], v[8:11], v[0:3], 0
	s_lshl_b64 s[84:85], s[84:85], 16
	s_mov_b64 s[86:87], s[38:39]
	s_add_u32 s84, s86, s84
	v_mfma_f32_16x16x32_bf16 v[8:11], v[8:11], v[4:7], 0
	s_addc_u32 s85, s87, s85
	s_add_i32 s2, s2, s88
	s_cmpk_lt_i32 s2, 0x804
	v_mfma_f32_16x16x32_bf16 v[20:23], v[16:19], v[0:3], 0
	v_mfma_f32_16x16x32_bf16 v[16:19], v[16:19], v[4:7], 0
	v_mfma_f32_16x16x32_bf16 v[170:173], v[24:27], v[0:3], 0
	v_mfma_f32_16x16x32_bf16 v[24:27], v[24:27], v[4:7], 0
	v_mfma_f32_16x16x32_bf16 v[178:181], v[174:177], v[0:3], 0
	v_mfma_f32_16x16x32_bf16 v[174:177], v[174:177], v[4:7], 0
	v_mfma_f32_16x16x32_bf16 v[186:189], v[182:185], v[0:3], 0
	v_mfma_f32_16x16x32_bf16 v[182:185], v[182:185], v[4:7], 0
	v_mfma_f32_16x16x32_bf16 v[194:197], v[190:193], v[0:3], 0
	v_mfma_f32_16x16x32_bf16 v[190:193], v[190:193], v[4:7], 0
	v_mfma_f32_16x16x32_bf16 v[202:205], v[198:201], v[0:3], 0
	v_mfma_f32_16x16x32_bf16 v[198:201], v[198:201], v[4:7], 0
	v_mfma_f32_16x16x32_bf16 v[0:3], v[206:209], v[0:3], 0
	v_mfma_f32_16x16x32_bf16 v[4:7], v[206:209], v[4:7], 0
	ds_read_b64_tr_b16 v[206:207], v108
	ds_read_b64_tr_b16 v[208:209], v109
	ds_read_b64_tr_b16 v[210:211], v110
	ds_read_b64_tr_b16 v[212:213], v111
	ds_read_b64_tr_b16 v[214:215], v112
	ds_read_b64_tr_b16 v[216:217], v113
	s_waitcnt lgkmcnt(0)
	s_nop 0
	v_mfma_f32_16x16x32_bf16 v[12:15], v[214:217], v[206:209], v[12:15]
	v_mfma_f32_16x16x32_bf16 v[8:11], v[214:217], v[210:213], v[8:11]
	ds_read_b64_tr_b16 v[214:215], v114
	ds_read_b64_tr_b16 v[216:217], v115
	s_waitcnt lgkmcnt(0)
	s_nop 0
	v_mfma_f32_16x16x32_bf16 v[20:23], v[214:217], v[206:209], v[20:23]
	v_mfma_f32_16x16x32_bf16 v[16:19], v[214:217], v[210:213], v[16:19]
	ds_read_b64_tr_b16 v[214:215], v116
	ds_read_b64_tr_b16 v[216:217], v117
	s_waitcnt lgkmcnt(0)
	s_nop 0
	v_mfma_f32_16x16x32_bf16 v[170:173], v[214:217], v[206:209], v[170:173]
	v_mfma_f32_16x16x32_bf16 v[24:27], v[214:217], v[210:213], v[24:27]
	ds_read_b64_tr_b16 v[214:215], v118
	ds_read_b64_tr_b16 v[216:217], v119
	s_waitcnt lgkmcnt(0)
	s_nop 0
	v_mfma_f32_16x16x32_bf16 v[178:181], v[214:217], v[206:209], v[178:181]
	v_mfma_f32_16x16x32_bf16 v[174:177], v[214:217], v[210:213], v[174:177]
	ds_read_b64_tr_b16 v[214:215], v120
	ds_read_b64_tr_b16 v[216:217], v121
	s_waitcnt lgkmcnt(0)
	s_nop 0
	v_mfma_f32_16x16x32_bf16 v[186:189], v[214:217], v[206:209], v[186:189]
	v_mfma_f32_16x16x32_bf16 v[182:185], v[214:217], v[210:213], v[182:185]
	ds_read_b64_tr_b16 v[214:215], v122
	ds_read_b64_tr_b16 v[216:217], v123
	s_waitcnt lgkmcnt(0)
	s_nop 0
	v_mfma_f32_16x16x32_bf16 v[194:197], v[214:217], v[206:209], v[194:197]
	v_mfma_f32_16x16x32_bf16 v[190:193], v[214:217], v[210:213], v[190:193]
	ds_read_b64_tr_b16 v[214:215], v124
	ds_read_b64_tr_b16 v[216:217], v125
	s_waitcnt lgkmcnt(0)
	s_nop 0
	v_mfma_f32_16x16x32_bf16 v[202:205], v[214:217], v[206:209], v[202:205]
	v_mfma_f32_16x16x32_bf16 v[198:201], v[214:217], v[210:213], v[198:201]
	ds_read_b64_tr_b16 v[214:215], v126
	ds_read_b64_tr_b16 v[216:217], v127
	s_waitcnt lgkmcnt(0)
	s_barrier
	v_cvt_pk_bf16_f32 v12, v12, v13
	v_cvt_pk_bf16_f32 v13, v14, v15
	ds_write_b64 v161, v[12:13]
	v_cvt_pk_bf16_f32 v8, v8, v9
	v_cvt_pk_bf16_f32 v9, v10, v11
	ds_write_b64 v161, v[8:9] offset:4352
	v_cvt_pk_bf16_f32 v8, v20, v21
	v_cvt_pk_bf16_f32 v9, v22, v23
	ds_write_b64 v161, v[8:9] offset:32
	v_cvt_pk_bf16_f32 v8, v16, v17
	v_cvt_pk_bf16_f32 v9, v18, v19
	ds_write_b64 v161, v[8:9] offset:4384
	v_cvt_pk_bf16_f32 v8, v170, v171
	v_cvt_pk_bf16_f32 v9, v172, v173
	ds_write_b64 v161, v[8:9] offset:64
	v_cvt_pk_bf16_f32 v8, v24, v25
	v_cvt_pk_bf16_f32 v9, v26, v27
	ds_write_b64 v161, v[8:9] offset:4416
	v_cvt_pk_bf16_f32 v8, v178, v179
	v_cvt_pk_bf16_f32 v9, v180, v181
	ds_write_b64 v161, v[8:9] offset:96
	v_cvt_pk_bf16_f32 v8, v174, v175
	v_cvt_pk_bf16_f32 v9, v176, v177
	ds_write_b64 v161, v[8:9] offset:4448
	v_cvt_pk_bf16_f32 v8, v186, v187
	v_cvt_pk_bf16_f32 v9, v188, v189
	ds_write_b64 v161, v[8:9] offset:128
	v_cvt_pk_bf16_f32 v8, v182, v183
	v_cvt_pk_bf16_f32 v9, v184, v185
	ds_write_b64 v161, v[8:9] offset:4480
	v_cvt_pk_bf16_f32 v8, v194, v195
	v_cvt_pk_bf16_f32 v9, v196, v197
	ds_write_b64 v161, v[8:9] offset:160
	v_cvt_pk_bf16_f32 v8, v190, v191
	v_cvt_pk_bf16_f32 v9, v192, v193
	v_mfma_f32_16x16x32_bf16 v[0:3], v[214:217], v[206:209], v[0:3]
	ds_write_b64 v161, v[8:9] offset:4512
	v_cvt_pk_bf16_f32 v8, v202, v203
	v_cvt_pk_bf16_f32 v9, v204, v205
	ds_write_b64 v161, v[8:9] offset:192
	v_cvt_pk_bf16_f32 v8, v198, v199
	v_cvt_pk_bf16_f32 v9, v200, v201
	ds_write_b64 v161, v[8:9] offset:4544
	v_cvt_pk_bf16_f32 v0, v0, v1
	v_cvt_pk_bf16_f32 v1, v2, v3
	v_mfma_f32_16x16x32_bf16 v[4:7], v[214:217], v[210:213], v[4:7]
	s_nop 3
	ds_write_b64 v161, v[0:1] offset:224
	v_cvt_pk_bf16_f32 v0, v4, v5
	v_cvt_pk_bf16_f32 v1, v6, v7
	ds_write_b64 v161, v[0:1] offset:4576
	s_waitcnt lgkmcnt(0)
	s_barrier
	v_lshl_add_u64 v[4:5], s[84:85], 0, v[36:37]
	ds_read_b128 v[0:3], v169
	s_waitcnt lgkmcnt(0)
	global_store_dwordx4 v[4:5], v[0:3], off sc1
	s_nop 1
	v_lshl_add_u64 v[4:5], s[84:85], 0, v[46:47]
	ds_read_b128 v[0:3], v162
	s_waitcnt lgkmcnt(0)
	global_store_dwordx4 v[4:5], v[0:3], off sc1
	s_nop 1
	v_lshl_add_u64 v[4:5], s[84:85], 0, v[48:49]
	ds_read_b128 v[0:3], v163
	s_waitcnt lgkmcnt(0)
	global_store_dwordx4 v[4:5], v[0:3], off sc1
	s_nop 1
	v_lshl_add_u64 v[4:5], s[84:85], 0, v[50:51]
	ds_read_b128 v[0:3], v164
	s_waitcnt lgkmcnt(0)
	global_store_dwordx4 v[4:5], v[0:3], off sc1
	s_nop 1
	v_lshl_add_u64 v[4:5], s[84:85], 0, v[52:53]
	ds_read_b128 v[0:3], v165
	s_waitcnt lgkmcnt(0)
	global_store_dwordx4 v[4:5], v[0:3], off sc1
	s_nop 1
	v_lshl_add_u64 v[4:5], s[84:85], 0, v[54:55]
	ds_read_b128 v[0:3], v166
	s_waitcnt lgkmcnt(0)
	global_store_dwordx4 v[4:5], v[0:3], off sc1
	s_nop 1
	v_lshl_add_u64 v[4:5], s[84:85], 0, v[56:57]
	ds_read_b128 v[0:3], v167
	s_waitcnt lgkmcnt(0)
	global_store_dwordx4 v[4:5], v[0:3], off sc1
	s_nop 1
	v_lshl_add_u64 v[4:5], s[84:85], 0, v[58:59]
	ds_read_b128 v[0:3], v168
	s_waitcnt lgkmcnt(0)
	global_store_dwordx4 v[4:5], v[0:3], off sc1
	s_nop 1
	s_barrier
	s_cbranch_scc0 .LBB0_641

.LBB0_793:
	s_nop 7
	v_cndmask_b32_e64 v40, v40, 0, s[48:49]
	v_cndmask_b32_e64 v41, 0, v41, s[50:51]
	v_cndmask_b32_e64 v42, v42, 0, s[52:53]
	v_cndmask_b32_e64 v43, v43, 0, s[54:55]
	v_cvt_pk_bf16_f32 v40, v40, v41
	v_cvt_pk_bf16_f32 v41, v42, v43
	ds_write_b64 v194, v[40:41] offset:32
	s_waitcnt lgkmcnt(0)
	s_barrier
	ds_read_b64_tr_b16 v[40:41], v184
	ds_read_b64_tr_b16 v[42:43], v185
	ds_read_b64_tr_b16 v[44:45], v186
	ds_read_b64_tr_b16 v[46:47], v187
	s_waitcnt lgkmcnt(0)
	ds_read_b128 v[64:67], v198 offset:4608
	ds_read_b128 v[48:51], v198
	ds_read_b128 v[56:59], v198 offset:2304
	s_waitcnt lgkmcnt(2)
	v_mfma_f32_16x16x32_bf16 v[76:79], v[40:43], v[64:67], 0
	s_andn2_b64 vcc, exec, s[70:71]
	v_mfma_f32_16x16x32_bf16 v[80:83], v[44:47], v[64:67], 0
	ds_read_b128 v[64:67], v199
	s_waitcnt lgkmcnt(2)
	v_mfma_f32_16x16x32_bf16 v[52:55], v[40:43], v[48:51], 0
	v_mfma_f32_16x16x32_bf16 v[48:51], v[44:47], v[48:51], 0
	s_waitcnt lgkmcnt(1)
	v_mfma_f32_16x16x32_bf16 v[60:63], v[40:43], v[56:59], 0
	v_mfma_f32_16x16x32_bf16 v[56:59], v[44:47], v[56:59], 0
	s_waitcnt lgkmcnt(0)
	v_mfma_f32_16x16x32_bf16 v[84:87], v[44:47], v[64:67], 0
	ds_read_b64_tr_b16 v[44:45], v188
	ds_read_b64_tr_b16 v[46:47], v189
	ds_read_b64_tr_b16 v[206:207], v190
	ds_read_b64_tr_b16 v[208:209], v191
	s_waitcnt lgkmcnt(0)
	v_mfma_f32_16x16x32_bf16 v[40:43], v[40:43], v[64:67], 0
	ds_read_b128 v[64:67], v198 offset:64
	s_waitcnt lgkmcnt(0)
	v_mfma_f32_16x16x32_bf16 v[68:71], v[44:47], v[64:67], v[52:55]
	v_mfma_f32_16x16x32_bf16 v[64:67], v[206:209], v[64:67], v[48:51]
	s_nop 2
	ds_read_b128 v[48:51], v198 offset:2368
	s_waitcnt lgkmcnt(0)
	v_mfma_f32_16x16x32_bf16 v[60:63], v[44:47], v[48:51], v[60:63]
	v_mfma_f32_16x16x32_bf16 v[56:59], v[206:209], v[48:51], v[56:59]
	ds_read_b128 v[48:51], v198 offset:4672
	s_waitcnt lgkmcnt(0)
	v_mfma_f32_16x16x32_bf16 v[52:55], v[44:47], v[48:51], v[76:79]
	s_nop 2
	ds_read_b128 v[76:79], v199 offset:64
	v_mfma_f32_16x16x32_bf16 v[48:51], v[206:209], v[48:51], v[80:83]
	s_waitcnt lgkmcnt(0)
	v_mfma_f32_16x16x32_bf16 v[44:47], v[44:47], v[76:79], v[40:43]
	v_mfma_f32_16x16x32_bf16 v[40:43], v[206:209], v[76:79], v[84:87]
	s_cbranch_vccnz .LBB0_795
	ds_read_b128 v[76:79], v200
	s_waitcnt lgkmcnt(0)
	v_mfma_f32_16x16x32_bf16 v[68:71], v[0:3], v[76:79], v[68:71]
	v_mfma_f32_16x16x32_bf16 v[64:67], v[4:7], v[76:79], v[64:67]
	ds_read_b128 v[76:79], v200 offset:4352
	s_waitcnt lgkmcnt(0)
	v_mfma_f32_16x16x32_bf16 v[60:63], v[0:3], v[76:79], v[60:63]
	v_mfma_f32_16x16x32_bf16 v[56:59], v[4:7], v[76:79], v[56:59]
	ds_read_b128 v[76:79], v200 offset:8704
	s_waitcnt lgkmcnt(0)
	v_mfma_f32_16x16x32_bf16 v[52:55], v[0:3], v[76:79], v[52:55]
	v_mfma_f32_16x16x32_bf16 v[48:51], v[4:7], v[76:79], v[48:51]
	ds_read_b128 v[76:79], v201
	s_waitcnt lgkmcnt(0)
	v_mfma_f32_16x16x32_bf16 v[44:47], v[0:3], v[76:79], v[44:47]
	v_mfma_f32_16x16x32_bf16 v[40:43], v[4:7], v[76:79], v[40:43]
	ds_read_b128 v[76:79], v200 offset:64
	s_waitcnt lgkmcnt(0)
	v_mfma_f32_16x16x32_bf16 v[68:71], v[8:11], v[76:79], v[68:71]
	v_mfma_f32_16x16x32_bf16 v[64:67], v[12:15], v[76:79], v[64:67]
	ds_read_b128 v[76:79], v200 offset:4416
	s_waitcnt lgkmcnt(0)
	v_mfma_f32_16x16x32_bf16 v[60:63], v[8:11], v[76:79], v[60:63]
	v_mfma_f32_16x16x32_bf16 v[56:59], v[12:15], v[76:79], v[56:59]
	ds_read_b128 v[76:79], v200 offset:8768
	s_waitcnt lgkmcnt(0)
	v_mfma_f32_16x16x32_bf16 v[52:55], v[8:11], v[76:79], v[52:55]
	v_mfma_f32_16x16x32_bf16 v[48:51], v[12:15], v[76:79], v[48:51]
	ds_read_b128 v[76:79], v201 offset:64
	s_waitcnt lgkmcnt(0)
	v_mfma_f32_16x16x32_bf16 v[44:47], v[8:11], v[76:79], v[44:47]
	v_mfma_f32_16x16x32_bf16 v[40:43], v[12:15], v[76:79], v[40:43]
	ds_read_b128 v[76:79], v200 offset:128
	s_waitcnt lgkmcnt(0)
	v_mfma_f32_16x16x32_bf16 v[68:71], v[16:19], v[76:79], v[68:71]
	v_mfma_f32_16x16x32_bf16 v[64:67], v[20:23], v[76:79], v[64:67]
	ds_read_b128 v[76:79], v200 offset:4480
	s_waitcnt lgkmcnt(0)
	v_mfma_f32_16x16x32_bf16 v[60:63], v[16:19], v[76:79], v[60:63]
	v_mfma_f32_16x16x32_bf16 v[56:59], v[20:23], v[76:79], v[56:59]
	ds_read_b128 v[76:79], v200 offset:8832
	s_waitcnt lgkmcnt(0)
	v_mfma_f32_16x16x32_bf16 v[52:55], v[16:19], v[76:79], v[52:55]
	v_mfma_f32_16x16x32_bf16 v[48:51], v[20:23], v[76:79], v[48:51]
	ds_read_b128 v[76:79], v201 offset:128
	s_waitcnt lgkmcnt(0)
	v_mfma_f32_16x16x32_bf16 v[44:47], v[16:19], v[76:79], v[44:47]
	v_mfma_f32_16x16x32_bf16 v[40:43], v[20:23], v[76:79], v[40:43]
	ds_read_b128 v[76:79], v200 offset:192
	s_waitcnt lgkmcnt(0)
	v_mfma_f32_16x16x32_bf16 v[68:71], v[24:27], v[76:79], v[68:71]
	v_mfma_f32_16x16x32_bf16 v[64:67], v[28:31], v[76:79], v[64:67]
	ds_read_b128 v[76:79], v200 offset:4544
	s_waitcnt lgkmcnt(0)
	v_mfma_f32_16x16x32_bf16 v[60:63], v[24:27], v[76:79], v[60:63]
	v_mfma_f32_16x16x32_bf16 v[56:59], v[28:31], v[76:79], v[56:59]
	ds_read_b128 v[76:79], v200 offset:8896
	s_waitcnt lgkmcnt(0)
	v_mfma_f32_16x16x32_bf16 v[52:55], v[24:27], v[76:79], v[52:55]
	v_mfma_f32_16x16x32_bf16 v[48:51], v[28:31], v[76:79], v[48:51]
	ds_read_b128 v[76:79], v201 offset:192
	s_waitcnt lgkmcnt(0)
	v_mfma_f32_16x16x32_bf16 v[44:47], v[24:27], v[76:79], v[44:47]
	v_mfma_f32_16x16x32_bf16 v[40:43], v[28:31], v[76:79], v[40:43]
